# v16: as v13 with ten mid-size heavy units per (b,h) moved to the front of the light queues
# speedup vs baseline: 1.0788x; 1.0059x over previous
; __global__ void __launch_bounds__(512) fwd_megakernel(Args a) {
;     ...
;             if (tq0_ == 0) { int slot = -1;
;                 while (tries < 8) { int len = (myq < 4) ? 64 : 192;
;     ...
;                     if (rep) len = 64;
;     ...
;                     if (rep) { if (myq < 4) len = 0; }
;     ...
;  const int idx = (int)atomicAdd(barw + BAR_QCTR + 64 * myq, 1u);
;     ...
;                     if (rep && myq >= 4 && idx < 64) continue;
;     ...
;                     if (idx < len) { slot = (myq << 16) | idx; break; } myq = (myq + 1) & 7; ++tries; }
;                 qslot[0] = slot; }
.LBB0_350:
	v_cmp_gt_i32_e32 vcc, 8, v239
	s_or_b64 s[24:25], s[24:25], exec
	s_and_saveexec_b64 s[26:27], vcc
	s_cbranch_execz .LBB0_349
	v_readlane_b32 s12, v254, 56
	v_lshlrev_b32_e32 v0, 6, v233
	v_readlane_b32 s13, v254, 57
	v_cmp_gt_i32_e32 vcc, 4, v233
	s_nop 0
	v_lshl_add_u64 v[4:5], v[0:1], 2, s[12:13]
	global_atomic_add v0, v[4:5], v231, off sc0
	v_and_b32_e32 v3, 1, v233
	v_lshlrev_b32_e32 v3, 6, v3
	v_add_u32_e32 v3, 0xaa, v3
	v_cndmask_b32_e64 v3, v3, 54, vcc
	s_waitcnt vmcnt(0)
	v_cmp_ge_i32_e32 vcc, v0, v3
	s_and_saveexec_b64 s[12:13], vcc
	s_xor_b64 s[36:37], exec, s[12:13]
	v_add_u32_e32 v4, 1, v233
	v_and_b32_e32 v233, 7, v4
	v_add_u32_e32 v239, 1, v239
	s_andn2_saveexec_b64 s[36:37], s[36:37]
	s_cbranch_execz .LBB0_348
	v_lshl_or_b32 v2, v233, 16, v0
	s_branch .LBB0_348

; __global__ void __launch_bounds__(512) fwd_megakernel(Args a) {
;     ...
;             __syncthreads();
;             const int slot = qslot[0];
;             if (slot < 0) break;
;             const int q = slot >> 16, idx = slot & 0xffff;
;             int ub, uh, uq; bool isdf = true;
;             if (q < 4) { ub = q >> 1; uh = 3 - (q & 1); uq = 63 - idx; }
;             else { const int y = q - 4;
;                 if (idx < 64) { ub = y >> 1; uh = 1 - (y & 1); uq = 63 - idx; }
;                 else { const int v = idx - 64; const int bh = 4 * y + (v & 3); ub = bh >> 3; uh = bh & 7; uq = 31 - (v >> 2); isdf = false; } }
.LBB0_356:
	s_or_b64 exec, exec, s[0:1]
	s_add_i32 s0, s4, 0
	v_mov_b32_e32 v0, s0
	s_waitcnt lgkmcnt(0)
	s_barrier
	ds_read_b32 v0, v0
	s_waitcnt lgkmcnt(0)
	v_cmp_gt_i32_e32 vcc, 0, v0
	v_readfirstlane_b32 s4, v0
	s_cbranch_vccnz .LBB0_370
	s_and_b32 s5, s4, 0xffff
	s_cmp_gt_u32 s4, 0x3ffff
	s_mov_b64 s[6:7], -1
	s_cbranch_scc0 .LBB0_367
	s_lshr_b32 s12, s4, 16
	s_add_i32 s12, s12, -4
	s_cmp_lt_u32 s5, 10
	s_cbranch_scc0 .Lmv_not
	s_lshr_b32 s14, s12, 1
	s_and_b32 s16, s12, 1
	s_sub_i32 s16, 3, s16
	s_sub_i32 s15, 31, s5
	s_mov_b64 s[0:1], -1
	s_branch .LBB0_369
.Lmv_not:
	s_add_i32 s5, s5, -10
	s_cmp_lt_u32 s5, 64
	s_cselect_b64 s[0:1], -1, 0
	s_cmp_gt_u32 s5, 63
	s_cbranch_scc0 .LBB0_360
	s_sub_i32 s6, s5, 64
	s_cmp_lt_u32 s6, 0x80
	s_cbranch_scc1 .Lsbq_own
	s_add_i32 s12, s12, -1
	s_add_i32 s6, s6, -32

; __global__ void __launch_bounds__(512) fwd_megakernel(Args a) {
;     ...
;             if (q < 4) { ub = q >> 1; uh = 3 - (q & 1); uq = 63 - idx; }
;             else { const int y = q - 4;
;                 if (idx < 64) { ub = y >> 1; uh = 1 - (y & 1); uq = 63 - idx; }
;                 else { const int v = idx - 64; const int bh = 4 * y + (v & 3); ub = bh >> 3; uh = bh & 7; uq = 31 - (v >> 2); isdf = false; } }
.LBB0_367:
	s_and_b64 vcc, exec, s[6:7]
	s_cbranch_vccz .LBB0_363
	s_bfe_u32 s0, s4, 0x10010
	s_lshr_b32 s14, s4, 17
	s_xor_b32 s16, s0, 3
	s_cmp_lt_u32 s5, 32
	s_cbranch_scc1 .Lhv_ok
	s_add_i32 s5, s5, 10
